# gla pass1 chunk loop: two redundant workgroup barriers per chunk removed (loop-top barrier directly after the loop-bottom one; post-state-update barrier, whose readers and the next raw-tile writes tou
# speedup vs baseline: 1.0036x; 1.0036x over previous
.LBB0_533:
	s_or_b64 exec, exec, s[12:13]
	ds_read_u16 v0, v100 offset:55040
	ds_read_u16 v1, v100 offset:55296
	v_add_u32_e32 v112, s45, v90
	s_add_i32 s10, s10, -1
	s_add_i32 s54, s54, 1
	s_cmp_eq_u32 s10, -2
	s_waitcnt lgkmcnt(0)
	v_lshl_or_b32 v0, v1, 16, v0
	ds_read_u16 v1, v100 offset:55552
	ds_read_u16 v2, v100 offset:55808
	s_waitcnt lgkmcnt(0)
	v_lshl_or_b32 v1, v2, 16, v1
	ds_read_u16 v2, v100 offset:56064
	ds_read_u16 v3, v100 offset:56320
	s_waitcnt lgkmcnt(0)
	v_lshl_or_b32 v2, v3, 16, v2
	ds_read_u16 v3, v100 offset:56576
	ds_read_u16 v4, v100 offset:56832
	s_waitcnt lgkmcnt(0)
	v_lshl_or_b32 v3, v4, 16, v3
	ds_read_u16 v4, v100 offset:57088
	ds_read_u16 v5, v100 offset:57344
	s_waitcnt lgkmcnt(0)
	v_lshl_or_b32 v4, v5, 16, v4
	ds_read_u16 v5, v100 offset:57600
	ds_read_u16 v6, v100 offset:57856
	s_waitcnt lgkmcnt(0)
	v_lshl_or_b32 v5, v6, 16, v5
	ds_read_u16 v6, v100 offset:58112
	ds_read_u16 v7, v100 offset:58368
	s_waitcnt lgkmcnt(0)
	v_lshl_or_b32 v6, v7, 16, v6
	ds_read_u16 v7, v100 offset:58624
	ds_read_u16 v8, v100 offset:58880
	s_waitcnt lgkmcnt(0)
	v_lshl_or_b32 v7, v8, 16, v7
	ds_write_b128 v101, v[0:3] offset:14336
	ds_write_b128 v101, v[4:7] offset:14352
	s_waitcnt lgkmcnt(0)
	s_barrier
	ds_read_b128 v[74:77], v102 offset:14336
	ds_read_b128 v[78:81], v102 offset:14368
	ds_read_b128 v[0:3], v103 offset:9216
	ds_read_b128 v[104:107], v103 offset:9248
	s_waitcnt lgkmcnt(1)
	v_mfma_f32_32x32x16_bf16 v[0:15], v[0:3], v[74:77], 0
	s_waitcnt lgkmcnt(0)
	v_mfma_f32_32x32x16_bf16 v[0:15], v[104:107], v[78:81], v[0:15]
	ds_read_b128 v[104:107], v112 offset:45568
	ds_read_b128 v[108:111], v112 offset:45600
	s_waitcnt lgkmcnt(1)
	s_nop 8
	v_pk_fma_f32 v[70:71], v[70:71], v[104:105], v[0:1]
	v_pk_fma_f32 v[68:69], v[68:69], v[106:107], v[2:3]
	ds_read_b128 v[0:3], v112 offset:45632
	s_waitcnt lgkmcnt(1)
	v_pk_fma_f32 v[64:65], v[64:65], v[108:109], v[4:5]
	v_pk_fma_f32 v[62:63], v[62:63], v[110:111], v[6:7]
	s_waitcnt lgkmcnt(0)
	v_pk_fma_f32 v[60:61], v[60:61], v[0:1], v[8:9]
	v_pk_fma_f32 v[58:59], v[58:59], v[2:3], v[10:11]
	ds_read_b128 v[0:3], v112 offset:45664
	s_waitcnt lgkmcnt(0)
	v_pk_fma_f32 v[56:57], v[56:57], v[0:1], v[12:13]
	v_pk_fma_f32 v[52:53], v[52:53], v[2:3], v[14:15]
	ds_read_b128 v[0:3], v103 offset:11776
	ds_read_b128 v[104:107], v103 offset:11808
	s_waitcnt lgkmcnt(1)
	v_mfma_f32_32x32x16_bf16 v[0:15], v[0:3], v[74:77], 0
	ds_read_b128 v[74:77], v112 offset:45696
	s_waitcnt lgkmcnt(1)
	v_mfma_f32_32x32x16_bf16 v[0:15], v[104:107], v[78:81], v[0:15]
	s_waitcnt lgkmcnt(0)
	s_nop 10
	v_pk_fma_f32 v[54:55], v[54:55], v[74:75], v[0:1]
	v_pk_fma_f32 v[50:51], v[50:51], v[76:77], v[2:3]
	ds_read_b128 v[0:3], v112 offset:45728
	s_waitcnt lgkmcnt(0)
	v_pk_fma_f32 v[48:49], v[48:49], v[0:1], v[4:5]
	v_pk_fma_f32 v[46:47], v[46:47], v[2:3], v[6:7]
	ds_read_b128 v[0:3], v112 offset:45760
	s_waitcnt lgkmcnt(0)
	v_pk_fma_f32 v[44:45], v[44:45], v[0:1], v[8:9]
	v_pk_fma_f32 v[40:41], v[40:41], v[2:3], v[10:11]
	ds_read_b128 v[0:3], v112 offset:45792
	s_waitcnt lgkmcnt(0)
	v_pk_fma_f32 v[38:39], v[38:39], v[0:1], v[12:13]
	v_pk_fma_f32 v[36:37], v[36:37], v[2:3], v[14:15]
	s_cbranch_scc1 .LBB0_542
.LBB0_534:
	s_waitcnt vmcnt(2)
	ds_write_b128 v92, v[16:19] offset:50944
	s_waitcnt vmcnt(1)
	ds_write_b128 v93, v[20:23] offset:55040
	s_waitcnt vmcnt(0)
	ds_write_b128 v94, v[24:27] offset:55040
	s_and_saveexec_b64 s[12:13], s[36:37]
	ds_write_b128 v95, v[28:31] offset:24576
	s_or_b64 exec, exec, s[12:13]
	s_cmp_eq_u32 s10, -1
	s_cbranch_scc1 .LBB0_540
	s_and_b64 s[12:13], s[0:1], exec
	s_cselect_b32 s12, s10, s54
	s_lshl_b32 s43, s12, 5
	s_add_i32 s43, s43, s51
	v_add_u32_e32 v0, s43, v84
	v_mad_i64_i32 v[0:1], s[12:13], v0, s94, v[66:67]
	v_add_u32_e32 v2, s43, v85
	v_mad_i64_i32 v[2:3], s[12:13], v2, s94, v[72:73]
	global_load_dwordx4 v[16:19], v[0:1], off offset:1536
	global_load_dwordx4 v[20:23], v[2:3], off offset:2048
	v_add_u32_e32 v0, s43, v86
	v_mad_i64_i32 v[0:1], s[12:13], v0, s94, v[72:73]
	global_load_dwordx4 v[24:27], v[0:1], off offset:2048
	s_and_saveexec_b64 s[12:13], s[36:37]
	s_cbranch_execz .LBB0_539
	v_add_u32_e32 v2, s43, v87
	v_mov_b64_e32 v[0:1], s[58:59]
	v_mad_i64_i32 v[0:1], s[72:73], v2, s94, v[0:1]
	v_lshl_add_u64 v[0:1], v[42:43], 1, v[0:1]
	v_add_co_u32_e32 v0, vcc, 0x1000, v0
	s_nop 1
	v_addc_co_u32_e32 v1, vcc, 0, v1, vcc
	global_load_dwordx4 v[28:31], v[0:1], off
